# grid barrier: follower WGs poll the top-level generation word directly (one relay hop fewer); per-XCD generation add dropped
# speedup vs baseline: 1.0071x; 1.0029x over previous
.LBB0_163:
	s_or_b64 exec, exec, s[6:7]
	v_cvt_f32_u32_e32 v4, v2
	s_waitcnt vmcnt(0)
	v_readfirstlane_b32 s4, v3
	v_sub_u32_e32 v3, 0, v2
	v_rcp_iflag_f32_e32 v4, v4
	v_add_u32_e32 v5, s4, v1
	v_mul_f32_e32 v4, 0x4f7ffffe, v4
	v_cvt_u32_f32_e32 v4, v4
	v_mul_lo_u32 v1, v3, v4
	v_mul_hi_u32 v1, v4, v1
	v_add_u32_e32 v1, v4, v1
	v_mul_hi_u32 v1, v5, v1
	v_mul_lo_u32 v3, v1, v2
	v_sub_u32_e32 v3, v5, v3
	v_add_u32_e32 v4, 1, v1
	v_cmp_ge_u32_e32 vcc, v3, v2
	s_nop 1
	v_cndmask_b32_e32 v1, v1, v4, vcc
	v_sub_u32_e32 v4, v3, v2
	v_cndmask_b32_e32 v3, v3, v4, vcc
	v_add_u32_e32 v4, 1, v1
	v_cmp_ge_u32_e32 vcc, v3, v2
	v_add_u32_e32 v3, 1, v5
	s_nop 0
	v_cndmask_b32_e32 v1, v1, v4, vcc
	v_mul_lo_u32 v4, v2, v1
	v_add_u32_e32 v2, v4, v2
	v_cmp_ne_u32_e32 vcc, v3, v2
	s_and_saveexec_b64 s[4:5], vcc
	s_xor_b64 s[4:5], exec, s[4:5]
	s_cbranch_execz .LBB0_177
	s_waitcnt lgkmcnt(0)
	v_mov_b32_e32 v0, 0
	s_add_u32 s10, s90, 0x3469600
	s_addc_u32 s11, s91, 0
	global_load_dword v0, v0, s[10:11] sc1
	s_waitcnt vmcnt(0)
	v_cmp_eq_u32_e32 vcc, v0, v1
	s_and_saveexec_b64 s[6:7], vcc
	s_cbranch_execz .LBB0_176
	s_add_u32 s8, s90, 0x3466300
	s_addc_u32 s9, s91, 0
	s_mov_b32 s22, 1
	s_mov_b64 s[12:13], 0
	v_mov_b32_e32 v0, 0
	s_branch .LBB0_167

.LBB0_194:
	s_or_b64 exec, exec, s[6:7]
	s_mov_b64 s[6:7], exec
	v_mbcnt_lo_u32_b32 v0, s6, 0
	v_mbcnt_hi_u32_b32 v0, s7, v0
	v_cmp_eq_u32_e32 vcc, 0, v0
	s_waitcnt vmcnt(0)
	buffer_inv sc1
	s_and_saveexec_b64 s[8:9], vcc
	s_cbranch_execz .LBB0_196
	s_bcnt1_i32_b64 s6, s[6:7]
	v_mov_b32_e32 v0, 0x2000
	v_mov_b32_e32 v1, s6
.LBB0_196:
	s_or_b64 exec, exec, s[8:9]
	s_waitcnt vmcnt(0)

.LBB0_254:
	s_or_b64 exec, exec, s[4:5]
	s_mov_b64 s[4:5], exec
	v_mbcnt_lo_u32_b32 v0, s4, 0
	v_mbcnt_hi_u32_b32 v0, s5, v0
	v_cmp_eq_u32_e32 vcc, 0, v0
	s_waitcnt vmcnt(0)
	buffer_inv sc1
	s_and_saveexec_b64 s[6:7], vcc
	s_cbranch_execz .LBB0_256
	s_bcnt1_i32_b64 s4, s[4:5]
	v_mov_b32_e32 v0, 0x2000
	v_mov_b32_e32 v1, s4
.LBB0_256:
	s_or_b64 exec, exec, s[6:7]
	s_waitcnt vmcnt(0)

.LBB0_497:
	s_or_b64 exec, exec, s[6:7]
	s_mov_b64 s[6:7], exec
	v_mbcnt_lo_u32_b32 v0, s6, 0
	v_mbcnt_hi_u32_b32 v0, s7, v0
	v_cmp_eq_u32_e32 vcc, 0, v0
	s_waitcnt vmcnt(0)
	buffer_inv sc1
	s_and_saveexec_b64 s[8:9], vcc
	s_cbranch_execz .LBB0_499
	s_bcnt1_i32_b64 s6, s[6:7]
	v_mov_b32_e32 v0, 0x2000
	v_mov_b32_e32 v1, s6
.LBB0_499:
	s_or_b64 exec, exec, s[8:9]
	s_waitcnt vmcnt(0)

.LBB0_537:
	s_or_b64 exec, exec, s[12:13]
	v_cvt_f32_u32_e32 v4, v2
	s_waitcnt vmcnt(0)
	v_readfirstlane_b32 s6, v3
	v_sub_u32_e32 v3, 0, v2
	v_rcp_iflag_f32_e32 v4, v4
	v_add_u32_e32 v5, s6, v1
	v_mul_f32_e32 v4, 0x4f7ffffe, v4
	v_cvt_u32_f32_e32 v4, v4
	v_mul_lo_u32 v1, v3, v4
	v_mul_hi_u32 v1, v4, v1
	v_add_u32_e32 v1, v4, v1
	v_mul_hi_u32 v1, v5, v1
	v_mul_lo_u32 v3, v1, v2
	v_sub_u32_e32 v3, v5, v3
	v_add_u32_e32 v4, 1, v1
	v_cmp_ge_u32_e32 vcc, v3, v2
	s_nop 1
	v_cndmask_b32_e32 v1, v1, v4, vcc
	v_sub_u32_e32 v4, v3, v2
	v_cndmask_b32_e32 v3, v3, v4, vcc
	v_add_u32_e32 v4, 1, v1
	v_cmp_ge_u32_e32 vcc, v3, v2
	v_add_u32_e32 v3, 1, v5
	s_nop 0
	v_cndmask_b32_e32 v1, v1, v4, vcc
	v_mul_lo_u32 v4, v2, v1
	v_add_u32_e32 v2, v4, v2
	v_cmp_ne_u32_e32 vcc, v3, v2
	s_and_saveexec_b64 s[6:7], vcc
	s_xor_b64 s[12:13], exec, s[6:7]
	s_cbranch_execz .LBB0_551
	s_waitcnt lgkmcnt(0)
	v_mov_b32_e32 v0, 0
	s_add_u32 s20, s90, 0x3469600
	s_addc_u32 s21, s91, 0
	global_load_dword v0, v0, s[20:21] sc1
	s_waitcnt vmcnt(0)
	v_cmp_eq_u32_e32 vcc, v0, v1
	s_and_saveexec_b64 s[14:15], vcc
	s_cbranch_execz .LBB0_550
	s_add_u32 s16, s90, 0x3466300
	s_addc_u32 s17, s91, 0
	s_mov_b32 s8, 1
	s_mov_b64 s[22:23], 0
	v_mov_b32_e32 v0, 0
	s_branch .LBB0_541

.LBB0_568:
	s_or_b64 exec, exec, s[14:15]
	s_mov_b64 s[6:7], exec
	v_mbcnt_lo_u32_b32 v0, s6, 0
	v_mbcnt_hi_u32_b32 v0, s7, v0
	v_cmp_eq_u32_e32 vcc, 0, v0
	s_waitcnt vmcnt(0)
	buffer_inv sc1
	s_and_saveexec_b64 s[14:15], vcc
	s_cbranch_execz .LBB0_570
	s_bcnt1_i32_b64 s6, s[6:7]
	v_mov_b32_e32 v0, 0x2000
	v_mov_b32_e32 v1, s6
.LBB0_570:
	s_or_b64 exec, exec, s[14:15]
	s_waitcnt vmcnt(0)

.LBB0_715:
	s_or_b64 exec, exec, s[10:11]
	v_cvt_f32_u32_e32 v4, v2
	s_waitcnt vmcnt(0)
	v_readfirstlane_b32 s6, v3
	v_sub_u32_e32 v3, 0, v2
	v_rcp_iflag_f32_e32 v4, v4
	v_add_u32_e32 v5, s6, v1
	v_mul_f32_e32 v4, 0x4f7ffffe, v4
	v_cvt_u32_f32_e32 v4, v4
	v_mul_lo_u32 v1, v3, v4
	v_mul_hi_u32 v1, v4, v1
	v_add_u32_e32 v1, v4, v1
	v_mul_hi_u32 v1, v5, v1
	v_mul_lo_u32 v3, v1, v2
	v_sub_u32_e32 v3, v5, v3
	v_add_u32_e32 v4, 1, v1
	v_cmp_ge_u32_e32 vcc, v3, v2
	s_nop 1
	v_cndmask_b32_e32 v1, v1, v4, vcc
	v_sub_u32_e32 v4, v3, v2
	v_cndmask_b32_e32 v3, v3, v4, vcc
	v_add_u32_e32 v4, 1, v1
	v_cmp_ge_u32_e32 vcc, v3, v2
	v_add_u32_e32 v3, 1, v5
	s_nop 0
	v_cndmask_b32_e32 v1, v1, v4, vcc
	v_mul_lo_u32 v4, v2, v1
	v_add_u32_e32 v2, v4, v2
	v_cmp_ne_u32_e32 vcc, v3, v2
	s_and_saveexec_b64 s[6:7], vcc
	s_xor_b64 s[10:11], exec, s[6:7]
	s_cbranch_execz .LBB0_729
	s_waitcnt lgkmcnt(0)
	v_mov_b32_e32 v0, 0
	s_add_u32 s16, s90, 0x3469600
	s_addc_u32 s17, s91, 0
	global_load_dword v0, v0, s[16:17] sc1
	s_waitcnt vmcnt(0)
	v_cmp_eq_u32_e32 vcc, v0, v1
	s_and_saveexec_b64 s[12:13], vcc
	s_cbranch_execz .LBB0_728
	s_add_u32 s14, s90, 0x3466300
	s_addc_u32 s15, s91, 0
	s_mov_b32 s18, 1
	s_mov_b64 s[20:21], 0
	v_mov_b32_e32 v0, 0
	s_branch .LBB0_719

.LBB0_746:
	s_or_b64 exec, exec, s[10:11]
	s_mov_b64 s[6:7], exec
	v_mbcnt_lo_u32_b32 v0, s6, 0
	v_mbcnt_hi_u32_b32 v0, s7, v0
	v_cmp_eq_u32_e32 vcc, 0, v0
	s_waitcnt vmcnt(0)
	buffer_inv sc1
	s_and_saveexec_b64 s[10:11], vcc
	s_cbranch_execz .LBB0_748
	s_bcnt1_i32_b64 s6, s[6:7]
	v_mov_b32_e32 v0, 0x2000
	v_mov_b32_e32 v1, s6
.LBB0_748:
	s_or_b64 exec, exec, s[10:11]
	s_waitcnt vmcnt(0)

.LBB0_851:
	s_or_b64 exec, exec, s[8:9]
	v_cvt_f32_u32_e32 v4, v2
	s_waitcnt vmcnt(0)
	v_readfirstlane_b32 s6, v3
	v_sub_u32_e32 v3, 0, v2
	v_rcp_iflag_f32_e32 v4, v4
	v_add_u32_e32 v5, s6, v1
	v_mul_f32_e32 v4, 0x4f7ffffe, v4
	v_cvt_u32_f32_e32 v4, v4
	v_mul_lo_u32 v1, v3, v4
	v_mul_hi_u32 v1, v4, v1
	v_add_u32_e32 v1, v4, v1
	v_mul_hi_u32 v1, v5, v1
	v_mul_lo_u32 v3, v1, v2
	v_sub_u32_e32 v3, v5, v3
	v_add_u32_e32 v4, 1, v1
	v_cmp_ge_u32_e32 vcc, v3, v2
	s_nop 1
	v_cndmask_b32_e32 v1, v1, v4, vcc
	v_sub_u32_e32 v4, v3, v2
	v_cndmask_b32_e32 v3, v3, v4, vcc
	v_add_u32_e32 v4, 1, v1
	v_cmp_ge_u32_e32 vcc, v3, v2
	v_add_u32_e32 v3, 1, v5
	s_nop 0
	v_cndmask_b32_e32 v1, v1, v4, vcc
	v_mul_lo_u32 v4, v2, v1
	v_add_u32_e32 v2, v4, v2
	v_cmp_ne_u32_e32 vcc, v3, v2
	s_and_saveexec_b64 s[6:7], vcc
	s_xor_b64 s[6:7], exec, s[6:7]
	s_cbranch_execz .LBB0_865
	s_waitcnt lgkmcnt(0)
	v_mov_b32_e32 v0, 0
	s_add_u32 s12, s90, 0x3469600
	s_addc_u32 s13, s91, 0
	global_load_dword v0, v0, s[12:13] sc1
	s_waitcnt vmcnt(0)
	v_cmp_eq_u32_e32 vcc, v0, v1
	s_and_saveexec_b64 s[8:9], vcc
	s_cbranch_execz .LBB0_864
	s_add_u32 s10, s90, 0x3466300
	s_addc_u32 s11, s91, 0
	s_mov_b32 s24, 1
	s_mov_b64 s[14:15], 0
	v_mov_b32_e32 v0, 0
	s_branch .LBB0_855

.LBB0_882:
	s_or_b64 exec, exec, s[8:9]
	s_mov_b64 s[8:9], exec
	v_mbcnt_lo_u32_b32 v0, s8, 0
	v_mbcnt_hi_u32_b32 v0, s9, v0
	v_cmp_eq_u32_e32 vcc, 0, v0
	s_waitcnt vmcnt(0)
	buffer_inv sc1
	s_and_saveexec_b64 s[10:11], vcc
	s_cbranch_execz .LBB0_884
	s_bcnt1_i32_b64 s8, s[8:9]
	v_mov_b32_e32 v0, 0x2000
	v_mov_b32_e32 v1, s8
.LBB0_884:
	s_or_b64 exec, exec, s[10:11]
	s_waitcnt vmcnt(0)

.LBB0_970:
	s_or_b64 exec, exec, s[6:7]
	s_mov_b64 s[6:7], exec
	v_mbcnt_lo_u32_b32 v0, s6, 0
	v_mbcnt_hi_u32_b32 v0, s7, v0
	v_cmp_eq_u32_e32 vcc, 0, v0
	s_waitcnt vmcnt(0)
	buffer_inv sc1
	s_and_saveexec_b64 s[8:9], vcc
	s_cbranch_execz .LBB0_972
	s_bcnt1_i32_b64 s6, s[6:7]
	v_mov_b32_e32 v0, 0x2000
	v_mov_b32_e32 v1, s6
.LBB0_972:
	s_or_b64 exec, exec, s[8:9]
	s_waitcnt vmcnt(0)

.LBB0_998:
	s_or_b64 exec, exec, s[8:9]
	v_cvt_f32_u32_e32 v4, v2
	s_waitcnt vmcnt(0)
	v_readfirstlane_b32 s6, v3
	v_sub_u32_e32 v3, 0, v2
	v_rcp_iflag_f32_e32 v4, v4
	v_add_u32_e32 v5, s6, v1
	v_mul_f32_e32 v4, 0x4f7ffffe, v4
	v_cvt_u32_f32_e32 v4, v4
	v_mul_lo_u32 v1, v3, v4
	v_mul_hi_u32 v1, v4, v1
	v_add_u32_e32 v1, v4, v1
	v_mul_hi_u32 v1, v5, v1
	v_mul_lo_u32 v3, v1, v2
	v_sub_u32_e32 v3, v5, v3
	v_add_u32_e32 v4, 1, v1
	v_cmp_ge_u32_e32 vcc, v3, v2
	s_nop 1
	v_cndmask_b32_e32 v1, v1, v4, vcc
	v_sub_u32_e32 v4, v3, v2
	v_cndmask_b32_e32 v3, v3, v4, vcc
	v_add_u32_e32 v4, 1, v1
	v_cmp_ge_u32_e32 vcc, v3, v2
	v_add_u32_e32 v3, 1, v5
	s_nop 0
	v_cndmask_b32_e32 v1, v1, v4, vcc
	v_mul_lo_u32 v4, v2, v1
	v_add_u32_e32 v2, v4, v2
	v_cmp_ne_u32_e32 vcc, v3, v2
	s_and_saveexec_b64 s[6:7], vcc
	s_xor_b64 s[6:7], exec, s[6:7]
	s_cbranch_execz .LBB0_1012
	s_waitcnt lgkmcnt(0)
	v_mov_b32_e32 v0, 0
	s_add_u32 s12, s90, 0x3469600
	s_addc_u32 s13, s91, 0
	global_load_dword v0, v0, s[12:13] sc1
	s_waitcnt vmcnt(0)
	v_cmp_eq_u32_e32 vcc, v0, v1
	s_and_saveexec_b64 s[8:9], vcc
	s_cbranch_execz .LBB0_1011
	s_add_u32 s10, s90, 0x3466300
	s_addc_u32 s11, s91, 0
	s_mov_b32 s26, 1
	s_mov_b64 s[14:15], 0
	v_mov_b32_e32 v0, 0
	s_branch .LBB0_1002

.LBB0_1029:
	s_or_b64 exec, exec, s[6:7]
	s_mov_b64 s[6:7], exec
	v_mbcnt_lo_u32_b32 v0, s6, 0
	v_mbcnt_hi_u32_b32 v0, s7, v0
	v_cmp_eq_u32_e32 vcc, 0, v0
	s_waitcnt vmcnt(0)
	buffer_inv sc1
	s_and_saveexec_b64 s[8:9], vcc
	s_cbranch_execz .LBB0_1031
	s_bcnt1_i32_b64 s6, s[6:7]
	v_mov_b32_e32 v0, 0x2000
	v_mov_b32_e32 v1, s6
.LBB0_1031:
	s_or_b64 exec, exec, s[8:9]
	s_waitcnt vmcnt(0)

.LBB0_1061:
	s_or_b64 exec, exec, s[8:9]
	v_cvt_f32_u32_e32 v4, v2
	s_waitcnt vmcnt(0)
	v_readfirstlane_b32 s6, v3
	v_sub_u32_e32 v3, 0, v2
	v_rcp_iflag_f32_e32 v4, v4
	v_add_u32_e32 v5, s6, v1
	v_mul_f32_e32 v4, 0x4f7ffffe, v4
	v_cvt_u32_f32_e32 v4, v4
	v_mul_lo_u32 v1, v3, v4
	v_mul_hi_u32 v1, v4, v1
	v_add_u32_e32 v1, v4, v1
	v_mul_hi_u32 v1, v5, v1
	v_mul_lo_u32 v3, v1, v2
	v_sub_u32_e32 v3, v5, v3
	v_add_u32_e32 v4, 1, v1
	v_cmp_ge_u32_e32 vcc, v3, v2
	s_nop 1
	v_cndmask_b32_e32 v1, v1, v4, vcc
	v_sub_u32_e32 v4, v3, v2
	v_cndmask_b32_e32 v3, v3, v4, vcc
	v_add_u32_e32 v4, 1, v1
	v_cmp_ge_u32_e32 vcc, v3, v2
	v_add_u32_e32 v3, 1, v5
	s_nop 0
	v_cndmask_b32_e32 v1, v1, v4, vcc
	v_mul_lo_u32 v4, v2, v1
	v_add_u32_e32 v2, v4, v2
	v_cmp_ne_u32_e32 vcc, v3, v2
	s_and_saveexec_b64 s[6:7], vcc
	s_xor_b64 s[6:7], exec, s[6:7]
	s_cbranch_execz .LBB0_1075
	s_waitcnt lgkmcnt(0)
	v_mov_b32_e32 v0, 0
	s_add_u32 s12, s90, 0x3469600
	s_addc_u32 s13, s91, 0
	global_load_dword v0, v0, s[12:13] sc1
	s_waitcnt vmcnt(0)
	v_cmp_eq_u32_e32 vcc, v0, v1
	s_and_saveexec_b64 s[8:9], vcc
	s_cbranch_execz .LBB0_1074
	s_add_u32 s10, s90, 0x3466300
	s_addc_u32 s11, s91, 0
	s_mov_b32 s28, 1
	s_mov_b64 s[14:15], 0
	v_mov_b32_e32 v0, 0
	s_branch .LBB0_1065

.LBB0_1092:
	s_or_b64 exec, exec, s[8:9]
	s_mov_b64 s[8:9], exec
	v_mbcnt_lo_u32_b32 v0, s8, 0
	v_mbcnt_hi_u32_b32 v0, s9, v0
	v_cmp_eq_u32_e32 vcc, 0, v0
	s_waitcnt vmcnt(0)
	buffer_inv sc1
	s_and_saveexec_b64 s[10:11], vcc
	s_cbranch_execz .LBB0_1094
	s_bcnt1_i32_b64 s8, s[8:9]
	v_mov_b32_e32 v0, 0x2000
	v_mov_b32_e32 v1, s8
.LBB0_1094:
	s_or_b64 exec, exec, s[10:11]
	s_waitcnt vmcnt(0)

.LBB0_1414:
	s_or_b64 exec, exec, s[8:9]
	v_cvt_f32_u32_e32 v4, v2
	s_waitcnt vmcnt(0)
	v_readfirstlane_b32 s6, v3
	v_sub_u32_e32 v3, 0, v2
	v_rcp_iflag_f32_e32 v4, v4
	v_add_u32_e32 v5, s6, v1
	v_mul_f32_e32 v4, 0x4f7ffffe, v4
	v_cvt_u32_f32_e32 v4, v4
	v_mul_lo_u32 v1, v3, v4
	v_mul_hi_u32 v1, v4, v1
	v_add_u32_e32 v1, v4, v1
	v_mul_hi_u32 v1, v5, v1
	v_mul_lo_u32 v3, v1, v2
	v_sub_u32_e32 v3, v5, v3
	v_add_u32_e32 v4, 1, v1
	v_cmp_ge_u32_e32 vcc, v3, v2
	s_nop 1
	v_cndmask_b32_e32 v1, v1, v4, vcc
	v_sub_u32_e32 v4, v3, v2
	v_cndmask_b32_e32 v3, v3, v4, vcc
	v_add_u32_e32 v4, 1, v1
	v_cmp_ge_u32_e32 vcc, v3, v2
	v_add_u32_e32 v3, 1, v5
	s_nop 0
	v_cndmask_b32_e32 v1, v1, v4, vcc
	v_mul_lo_u32 v4, v2, v1
	v_add_u32_e32 v2, v4, v2
	v_cmp_ne_u32_e32 vcc, v3, v2
	s_and_saveexec_b64 s[6:7], vcc
	s_xor_b64 s[6:7], exec, s[6:7]
	s_cbranch_execz .LBB0_1428
	s_waitcnt lgkmcnt(0)
	v_mov_b32_e32 v0, 0
	s_add_u32 s12, s90, 0x3469600
	s_addc_u32 s13, s91, 0
	global_load_dword v0, v0, s[12:13] sc1
	s_waitcnt vmcnt(0)
	v_cmp_eq_u32_e32 vcc, v0, v1
	s_and_saveexec_b64 s[8:9], vcc
	s_cbranch_execz .LBB0_1427
	s_add_u32 s10, s90, 0x3466300
	s_addc_u32 s11, s91, 0
	s_mov_b32 s30, 1
	s_mov_b64 s[14:15], 0
	v_mov_b32_e32 v0, 0
	s_branch .LBB0_1418

.LBB0_1445:
	s_or_b64 exec, exec, s[6:7]
	s_mov_b64 s[6:7], exec
	v_mbcnt_lo_u32_b32 v0, s6, 0
	v_mbcnt_hi_u32_b32 v0, s7, v0
	v_cmp_eq_u32_e32 vcc, 0, v0
	s_waitcnt vmcnt(0)
	buffer_inv sc1
	s_and_saveexec_b64 s[8:9], vcc
	s_cbranch_execz .LBB0_1447
	s_bcnt1_i32_b64 s6, s[6:7]
	v_mov_b32_e32 v0, 0x2000
	v_mov_b32_e32 v1, s6
.LBB0_1447:
	s_or_b64 exec, exec, s[8:9]
	s_waitcnt vmcnt(0)

.LBB0_1473:
	s_or_b64 exec, exec, s[8:9]
	v_cvt_f32_u32_e32 v4, v2
	s_waitcnt vmcnt(0)
	v_readfirstlane_b32 s6, v3
	v_sub_u32_e32 v3, 0, v2
	v_rcp_iflag_f32_e32 v4, v4
	v_add_u32_e32 v5, s6, v1
	v_mul_f32_e32 v4, 0x4f7ffffe, v4
	v_cvt_u32_f32_e32 v4, v4
	v_mul_lo_u32 v1, v3, v4
	v_mul_hi_u32 v1, v4, v1
	v_add_u32_e32 v1, v4, v1
	v_mul_hi_u32 v1, v5, v1
	v_mul_lo_u32 v3, v1, v2
	v_sub_u32_e32 v3, v5, v3
	v_add_u32_e32 v4, 1, v1
	v_cmp_ge_u32_e32 vcc, v3, v2
	s_nop 1
	v_cndmask_b32_e32 v1, v1, v4, vcc
	v_sub_u32_e32 v4, v3, v2
	v_cndmask_b32_e32 v3, v3, v4, vcc
	v_add_u32_e32 v4, 1, v1
	v_cmp_ge_u32_e32 vcc, v3, v2
	v_add_u32_e32 v3, 1, v5
	s_nop 0
	v_cndmask_b32_e32 v1, v1, v4, vcc
	v_mul_lo_u32 v4, v2, v1
	v_add_u32_e32 v2, v4, v2
	v_cmp_ne_u32_e32 vcc, v3, v2
	s_and_saveexec_b64 s[6:7], vcc
	s_xor_b64 s[6:7], exec, s[6:7]
	s_cbranch_execz .LBB0_1487
	s_waitcnt lgkmcnt(0)
	v_mov_b32_e32 v0, 0
	s_add_u32 s12, s90, 0x3469600
	s_addc_u32 s13, s91, 0
	global_load_dword v0, v0, s[12:13] sc1
	s_waitcnt vmcnt(0)
	v_cmp_eq_u32_e32 vcc, v0, v1
	s_and_saveexec_b64 s[8:9], vcc
	s_cbranch_execz .LBB0_1486
	s_add_u32 s10, s90, 0x3466300
	s_addc_u32 s11, s91, 0
	s_mov_b32 s36, 1
	s_mov_b64 s[14:15], 0
	v_mov_b32_e32 v0, 0
	s_branch .LBB0_1477

.LBB0_1504:
	s_or_b64 exec, exec, s[6:7]
	s_mov_b64 s[6:7], exec
	v_mbcnt_lo_u32_b32 v0, s6, 0
	v_mbcnt_hi_u32_b32 v0, s7, v0
	v_cmp_eq_u32_e32 vcc, 0, v0
	s_waitcnt vmcnt(0)
	buffer_inv sc1
	s_and_saveexec_b64 s[8:9], vcc
	s_cbranch_execz .LBB0_1506
	s_bcnt1_i32_b64 s6, s[6:7]
	v_mov_b32_e32 v0, 0x2000
	v_mov_b32_e32 v1, s6
.LBB0_1506:
	s_or_b64 exec, exec, s[8:9]
	s_waitcnt vmcnt(0)

.LBB0_1745:
	s_or_b64 exec, exec, s[10:11]
	v_cvt_f32_u32_e32 v4, v2
	s_waitcnt vmcnt(0)
	v_readfirstlane_b32 s8, v3
	v_sub_u32_e32 v3, 0, v2
	v_rcp_iflag_f32_e32 v4, v4
	v_add_u32_e32 v5, s8, v1
	v_mul_f32_e32 v4, 0x4f7ffffe, v4
	v_cvt_u32_f32_e32 v4, v4
	v_mul_lo_u32 v1, v3, v4
	v_mul_hi_u32 v1, v4, v1
	v_add_u32_e32 v1, v4, v1
	v_mul_hi_u32 v1, v5, v1
	v_mul_lo_u32 v3, v1, v2
	v_sub_u32_e32 v3, v5, v3
	v_add_u32_e32 v4, 1, v1
	v_cmp_ge_u32_e32 vcc, v3, v2
	s_nop 1
	v_cndmask_b32_e32 v1, v1, v4, vcc
	v_sub_u32_e32 v4, v3, v2
	v_cndmask_b32_e32 v3, v3, v4, vcc
	v_add_u32_e32 v4, 1, v1
	v_cmp_ge_u32_e32 vcc, v3, v2
	v_add_u32_e32 v3, 1, v5
	s_nop 0
	v_cndmask_b32_e32 v1, v1, v4, vcc
	v_mul_lo_u32 v4, v2, v1
	v_add_u32_e32 v2, v4, v2
	v_cmp_ne_u32_e32 vcc, v3, v2
	s_and_saveexec_b64 s[8:9], vcc
	s_xor_b64 s[8:9], exec, s[8:9]
	s_cbranch_execz .LBB0_1759
	s_waitcnt lgkmcnt(0)
	v_mov_b32_e32 v0, 0
	s_add_u32 s14, s90, 0x3469600
	s_addc_u32 s15, s91, 0
	global_load_dword v0, v0, s[14:15] sc1
	s_waitcnt vmcnt(0)
	v_cmp_eq_u32_e32 vcc, v0, v1
	s_and_saveexec_b64 s[10:11], vcc
	s_cbranch_execz .LBB0_1758
	s_add_u32 s12, s90, 0x3466300
	s_addc_u32 s13, s91, 0
	s_mov_b32 s40, 1
	s_mov_b64 s[18:19], 0
	v_mov_b32_e32 v0, 0
	s_branch .LBB0_1749

.LBB0_1776:
	s_or_b64 exec, exec, s[10:11]
	s_mov_b64 s[10:11], exec
	v_mbcnt_lo_u32_b32 v0, s10, 0
	v_mbcnt_hi_u32_b32 v0, s11, v0
	v_cmp_eq_u32_e32 vcc, 0, v0
	s_waitcnt vmcnt(0)
	buffer_inv sc1
	s_and_saveexec_b64 s[12:13], vcc
	s_cbranch_execz .LBB0_1778
	s_bcnt1_i32_b64 s10, s[10:11]
	v_mov_b32_e32 v0, 0x2000
	v_mov_b32_e32 v1, s10
.LBB0_1778:
	s_or_b64 exec, exec, s[12:13]
	s_waitcnt vmcnt(0)

.LBB0_1836:
	s_or_b64 exec, exec, s[8:9]
	v_cvt_f32_u32_e32 v4, v2
	s_waitcnt vmcnt(0)
	v_readfirstlane_b32 s4, v3
	v_sub_u32_e32 v3, 0, v2
	v_rcp_iflag_f32_e32 v4, v4
	v_add_u32_e32 v5, s4, v1
	v_mul_f32_e32 v4, 0x4f7ffffe, v4
	v_cvt_u32_f32_e32 v4, v4
	v_mul_lo_u32 v1, v3, v4
	v_mul_hi_u32 v1, v4, v1
	v_add_u32_e32 v1, v4, v1
	v_mul_hi_u32 v1, v5, v1
	v_mul_lo_u32 v3, v1, v2
	v_sub_u32_e32 v3, v5, v3
	v_add_u32_e32 v4, 1, v1
	v_cmp_ge_u32_e32 vcc, v3, v2
	s_nop 1
	v_cndmask_b32_e32 v1, v1, v4, vcc
	v_sub_u32_e32 v4, v3, v2
	v_cndmask_b32_e32 v3, v3, v4, vcc
	v_add_u32_e32 v4, 1, v1
	v_cmp_ge_u32_e32 vcc, v3, v2
	v_add_u32_e32 v3, 1, v5
	s_nop 0
	v_cndmask_b32_e32 v1, v1, v4, vcc
	v_mul_lo_u32 v4, v2, v1
	v_add_u32_e32 v2, v4, v2
	v_cmp_ne_u32_e32 vcc, v3, v2
	s_and_saveexec_b64 s[4:5], vcc
	s_xor_b64 s[4:5], exec, s[4:5]
	s_cbranch_execz .LBB0_1850
	s_waitcnt lgkmcnt(0)
	v_mov_b32_e32 v0, 0
	s_add_u32 s12, s90, 0x3469600
	s_addc_u32 s13, s91, 0
	global_load_dword v0, v0, s[12:13] sc1
	s_waitcnt vmcnt(0)
	v_cmp_eq_u32_e32 vcc, v0, v1
	s_and_saveexec_b64 s[8:9], vcc
	s_cbranch_execz .LBB0_1849
	s_add_u32 s10, s90, 0x3466300
	s_addc_u32 s11, s91, 0
	s_mov_b32 s36, 1
	s_mov_b64 s[14:15], 0
	v_mov_b32_e32 v0, 0
	s_branch .LBB0_1840

.LBB0_1867:
	s_or_b64 exec, exec, s[8:9]
	s_mov_b64 s[8:9], exec
	v_mbcnt_lo_u32_b32 v0, s8, 0
	v_mbcnt_hi_u32_b32 v0, s9, v0
	v_cmp_eq_u32_e32 vcc, 0, v0
	s_waitcnt vmcnt(0)
	buffer_inv sc1
	s_and_saveexec_b64 s[10:11], vcc
	s_cbranch_execz .LBB0_1869
	s_bcnt1_i32_b64 s8, s[8:9]
	v_mov_b32_e32 v0, 0x2000
	v_mov_b32_e32 v1, s8
.LBB0_1869:
	s_or_b64 exec, exec, s[10:11]
	s_waitcnt vmcnt(0)

.LBB0_2219:
	s_or_b64 exec, exec, s[6:7]
	s_mov_b64 s[6:7], exec
	v_mbcnt_lo_u32_b32 v0, s6, 0
	v_mbcnt_hi_u32_b32 v0, s7, v0
	v_cmp_eq_u32_e32 vcc, 0, v0
	s_waitcnt vmcnt(0)
	buffer_inv sc1
	s_and_saveexec_b64 s[8:9], vcc
	s_cbranch_execz .LBB0_2221
	s_bcnt1_i32_b64 s6, s[6:7]
	v_mov_b32_e32 v0, 0x2000
	v_mov_b32_e32 v1, s6
.LBB0_2221:
	s_or_b64 exec, exec, s[8:9]
	s_waitcnt vmcnt(0)

.LBB0_2278:
	s_or_b64 exec, exec, s[6:7]
	s_mov_b64 s[6:7], exec
	v_mbcnt_lo_u32_b32 v0, s6, 0
	v_mbcnt_hi_u32_b32 v0, s7, v0
	v_cmp_eq_u32_e32 vcc, 0, v0
	s_waitcnt vmcnt(0)
	buffer_inv sc1
	s_and_saveexec_b64 s[8:9], vcc
	s_cbranch_execz .LBB0_2280
	s_bcnt1_i32_b64 s6, s[6:7]
	v_mov_b32_e32 v0, 0x2000
	v_mov_b32_e32 v1, s6
.LBB0_2280:
	s_or_b64 exec, exec, s[8:9]
	s_waitcnt vmcnt(0)

.LBB0_2341:
	s_or_b64 exec, exec, s[8:9]
	s_mov_b64 s[8:9], exec
	v_mbcnt_lo_u32_b32 v0, s8, 0
	v_mbcnt_hi_u32_b32 v0, s9, v0
	v_cmp_eq_u32_e32 vcc, 0, v0
	s_waitcnt vmcnt(0)
	buffer_inv sc1
	s_and_saveexec_b64 s[10:11], vcc
	s_cbranch_execz .LBB0_2343
	s_bcnt1_i32_b64 s8, s[8:9]
	v_mov_b32_e32 v0, 0x2000
	v_mov_b32_e32 v1, s8
.LBB0_2343:
	s_or_b64 exec, exec, s[10:11]
	s_waitcnt vmcnt(0)

.LBB0_2693:
	s_or_b64 exec, exec, s[4:5]
	s_mov_b64 s[4:5], exec
	v_mbcnt_lo_u32_b32 v0, s4, 0
	v_mbcnt_hi_u32_b32 v0, s5, v0
	v_cmp_eq_u32_e32 vcc, 0, v0
	s_waitcnt vmcnt(0)
	buffer_inv sc1
	s_and_saveexec_b64 s[6:7], vcc
	s_cbranch_execz .LBB0_2695
	s_bcnt1_i32_b64 s4, s[4:5]
	v_mov_b32_e32 v0, 0x2000
	v_mov_b32_e32 v1, s4
.LBB0_2695:
	s_or_b64 exec, exec, s[6:7]
	s_waitcnt vmcnt(0)
